# idx: validity masking / final mask / tie pass restricted to register groups holding slots <= t; previous unit's mask stores left in flight
# baseline (speedup 1.0000x reference)
.LBB0_810:
	v_readlane_b32 s0, v252, 1
	v_readlane_b32 s1, v252, 2
	s_bitcmp0_b32 s34, 0
	v_readlane_b32 s1, v252, 0
	v_readlane_b32 s4, v253, 26
	s_mul_i32 s0, s34, s0
	s_cselect_b32 s1, s1, s4
	s_add_i32 s0, s1, s0
	s_cmpk_gt_i32 s0, 0x3ff
	s_cbranch_scc1 .LBB0_809
	s_lshr_b32 s1, s0, 3
	s_and_b32 s5, s0, 7
	s_sub_i32 s4, 0x7f, s1
	s_lshl_b32 s33, s4, 4
	s_lshl_b32 s28, s5, 11
	s_add_i32 s6, s33, s28
	v_readlane_b32 s5, v252, 5
	v_and_b32_e32 v0, 15, v197
	v_lshrrev_b32_e32 v1, 4, v197
	v_add_u32_e32 v242, s6, v0
	v_lshlrev_b32_e32 v2, 4, v1
	v_lshl_add_u32 v243, v242, 9, v2
	v_lshlrev_b32_e32 v244, 6, v242
	v_add_u32_e32 v3, s28, v0
	v_lshl_add_u32 v245, v3, 7, v2
	s_lshr_b32 s5, s5, 6
	s_add_u32 s36, s40, 0x10e00000
	s_addc_u32 s37, s41, 0
	s_add_u32 s38, s40, 0x12e00000
	s_addc_u32 s39, s41, 0
	s_add_u32 s42, s40, 0x11600000
	s_addc_u32 s43, s41, 0
	s_lshl_b32 s7, s5, 2
	s_lshl_b32 s0, s5, 13
	v_add_u32_e32 v245, s0, v245
	v_add_u32_e32 v246, 0x1000, v245
	v_mov_b32_e32 v3, 0x2010
	v_mul_lo_u32 v247, v0, v3
	v_lshl_add_u32 v247, v1, 4, v247
	s_lshl_b32 s0, s7, 6
	v_add_u32_e32 v247, s0, v247
	s_waitcnt lgkmcnt(0)
	global_load_dwordx4 v[0:3], v243, s[36:37]
	global_load_dwordx4 v[4:7], v243, s[36:37] offset:64
	global_load_dwordx4 v[8:11], v243, s[36:37] offset:128
	global_load_dwordx4 v[12:15], v243, s[36:37] offset:192
	global_load_dwordx4 v[16:19], v243, s[36:37] offset:256
	global_load_dwordx4 v[20:23], v243, s[36:37] offset:320
	global_load_dwordx4 v[24:27], v243, s[36:37] offset:384
	global_load_dwordx4 v[28:31], v243, s[36:37] offset:448
	global_load_dwordx4 v[164:167], v244, s[38:39] offset:32
	s_sub_i32 s0, s4, s7
	s_cmp_lt_i32 s0, 0
	s_cbranch_scc1 .LBB0_820
	s_lshr_b32 s0, s0, 5
	s_cmp_eq_u32 s0, 0
	s_cbranch_scc1 .Lsc_g1
	s_cmp_eq_u32 s0, 1
	s_cbranch_scc1 .Lsc_g2
	s_cmp_eq_u32 s0, 2
	s_cbranch_scc1 .Lsc_g3

.Lsel_row:
	s_or_b32 s27, s26, s4
	s_mul_i32 s0, s27, 0x2010
	v_add_u32_e32 v145, s0, v152
	s_add_i32 s27, s27, s33
	s_lshr_b32 s46, s27, 8
	s_add_i32 s46, s46, 1
	s_lshl_b32 s47, s46, 8
	s_sub_i32 s47, 0x800, s47
	ds_read2st64_b32 v[102:103], v145 offset0:0 offset1:1
	ds_read2st64_b32 v[104:105], v145 offset0:2 offset1:3
	ds_read2st64_b32 v[106:107], v145 offset0:4 offset1:5
	ds_read2st64_b32 v[108:109], v145 offset0:6 offset1:7
	ds_read2st64_b32 v[110:111], v145 offset0:8 offset1:9
	ds_read2st64_b32 v[112:113], v145 offset0:10 offset1:11
	ds_read2st64_b32 v[114:115], v145 offset0:12 offset1:13
	ds_read2st64_b32 v[116:117], v145 offset0:14 offset1:15
	ds_read2st64_b32 v[118:119], v145 offset0:16 offset1:17
	ds_read2st64_b32 v[120:121], v145 offset0:18 offset1:19
	ds_read2st64_b32 v[122:123], v145 offset0:20 offset1:21
	ds_read2st64_b32 v[124:125], v145 offset0:22 offset1:23
	ds_read2st64_b32 v[126:127], v145 offset0:24 offset1:25
	ds_read2st64_b32 v[128:129], v145 offset0:26 offset1:27
	ds_read2st64_b32 v[130:131], v145 offset0:28 offset1:29
	ds_read2st64_b32 v[132:133], v145 offset0:30 offset1:31
	v_sub_u32_e32 v143, s27, v197
	v_ashrrev_i32_e32 v143, 6, v143
	v_lshlrev_b32_e64 v151, v143, -2
	v_not_b32_e32 v151, v151
	v_ashrrev_i32_e32 v144, 31, v143
	v_bfi_b32 v151, v144, 0, v151
	s_waitcnt lgkmcnt(0)
	s_cmp_lg_u32 s46, 1
	s_cbranch_scc1 .Lsel_nomask0
	v_bfe_i32 v134, v151, 0, 1
	v_bfi_b32 v102, v134, v102, v149
	v_bfe_i32 v135, v151, 1, 1
	v_bfi_b32 v103, v135, v103, v149
	v_bfe_i32 v134, v151, 2, 1
	v_bfi_b32 v104, v134, v104, v149
	v_bfe_i32 v135, v151, 3, 1
	v_bfi_b32 v105, v135, v105, v149
.Lsel_nomask0:
	s_cmp_lg_u32 s46, 2
	s_cbranch_scc1 .Lsel_nomask1
	v_bfe_i32 v134, v151, 4, 1
	v_bfi_b32 v106, v134, v106, v149
	v_bfe_i32 v135, v151, 5, 1
	v_bfi_b32 v107, v135, v107, v149
	v_bfe_i32 v134, v151, 6, 1
	v_bfi_b32 v108, v134, v108, v149
	v_bfe_i32 v135, v151, 7, 1
	v_bfi_b32 v109, v135, v109, v149
.Lsel_nomask1:
	s_cmp_lg_u32 s46, 3
	s_cbranch_scc1 .Lsel_nomask2
	v_bfe_i32 v134, v151, 8, 1
	v_bfi_b32 v110, v134, v110, v149
	v_bfe_i32 v135, v151, 9, 1
	v_bfi_b32 v111, v135, v111, v149
	v_bfe_i32 v134, v151, 10, 1
	v_bfi_b32 v112, v134, v112, v149
	v_bfe_i32 v135, v151, 11, 1
	v_bfi_b32 v113, v135, v113, v149
.Lsel_nomask2:
	s_cmp_lg_u32 s46, 4
	s_cbranch_scc1 .Lsel_nomask3
	v_bfe_i32 v134, v151, 12, 1
	v_bfi_b32 v114, v134, v114, v149
	v_bfe_i32 v135, v151, 13, 1
	v_bfi_b32 v115, v135, v115, v149
	v_bfe_i32 v134, v151, 14, 1
	v_bfi_b32 v116, v134, v116, v149
	v_bfe_i32 v135, v151, 15, 1
	v_bfi_b32 v117, v135, v117, v149
.Lsel_nomask3:
	s_cmp_lg_u32 s46, 5
	s_cbranch_scc1 .Lsel_nomask4
	v_bfe_i32 v134, v151, 16, 1
	v_bfi_b32 v118, v134, v118, v149
	v_bfe_i32 v135, v151, 17, 1
	v_bfi_b32 v119, v135, v119, v149
	v_bfe_i32 v134, v151, 18, 1
	v_bfi_b32 v120, v134, v120, v149
	v_bfe_i32 v135, v151, 19, 1
	v_bfi_b32 v121, v135, v121, v149
.Lsel_nomask4:
	s_cmp_lg_u32 s46, 6
	s_cbranch_scc1 .Lsel_nomask5
	v_bfe_i32 v134, v151, 20, 1
	v_bfi_b32 v122, v134, v122, v149
	v_bfe_i32 v135, v151, 21, 1
	v_bfi_b32 v123, v135, v123, v149
	v_bfe_i32 v134, v151, 22, 1
	v_bfi_b32 v124, v134, v124, v149
	v_bfe_i32 v135, v151, 23, 1
	v_bfi_b32 v125, v135, v125, v149
.Lsel_nomask5:
	s_cmp_lg_u32 s46, 7
	s_cbranch_scc1 .Lsel_nomask6
	v_bfe_i32 v134, v151, 24, 1
	v_bfi_b32 v126, v134, v126, v149
	v_bfe_i32 v135, v151, 25, 1
	v_bfi_b32 v127, v135, v127, v149
	v_bfe_i32 v134, v151, 26, 1
	v_bfi_b32 v128, v134, v128, v149
	v_bfe_i32 v135, v151, 27, 1
	v_bfi_b32 v129, v135, v129, v149
.Lsel_nomask6:
	s_cmp_lg_u32 s46, 8
	s_cbranch_scc1 .Lsel_nomask7
	v_bfe_i32 v134, v151, 28, 1
	v_bfi_b32 v130, v134, v130, v149
	v_bfe_i32 v135, v151, 29, 1
	v_bfi_b32 v131, v135, v131, v149
	v_bfe_i32 v134, v151, 30, 1
	v_bfi_b32 v132, v134, v132, v149
	v_bfe_i32 v135, v151, 31, 1
	v_bfi_b32 v133, v135, v133, v149
.Lsel_nomask7:
	s_cmpk_gt_i32 s27, 0xff
	s_cbranch_scc1 .Lsel_search
	s_mov_b32 s0, 0xd1400000
	s_branch .Lsel_mask

.Lsel_mask:
	v_mov_b32_e32 v142, s0
	v_mul_f32_e32 v142, s37, v142
	v_mov_b32_e32 v147, 0
	v_mov_b32_e32 v148, 0
	v_fma_f32 v134, v102, s36, v142 clamp
	v_fmamk_f32 v147, v134, 0x3f800000, v147
	v_fma_f32 v135, v103, s36, v142 clamp
	v_fmamk_f32 v147, v135, 0x40000000, v147
	v_fma_f32 v136, v104, s36, v142 clamp
	v_fmamk_f32 v147, v136, 0x40800000, v147
	v_fma_f32 v137, v105, s36, v142 clamp
	v_fmamk_f32 v147, v137, 0x41000000, v147
	s_cmp_eq_u32 s46, 1
	s_cbranch_scc1 .Lsel_mask_fin
	v_fma_f32 v134, v106, s36, v142 clamp
	v_fmamk_f32 v147, v134, 0x41800000, v147
	v_fma_f32 v135, v107, s36, v142 clamp
	v_fmamk_f32 v147, v135, 0x42000000, v147
	v_fma_f32 v136, v108, s36, v142 clamp
	v_fmamk_f32 v147, v136, 0x42800000, v147
	v_fma_f32 v137, v109, s36, v142 clamp
	v_fmamk_f32 v147, v137, 0x43000000, v147
	s_cmp_eq_u32 s46, 2
	s_cbranch_scc1 .Lsel_mask_fin
	v_fma_f32 v134, v110, s36, v142 clamp
	v_fmamk_f32 v147, v134, 0x43800000, v147
	v_fma_f32 v135, v111, s36, v142 clamp
	v_fmamk_f32 v147, v135, 0x44000000, v147
	v_fma_f32 v136, v112, s36, v142 clamp
	v_fmamk_f32 v147, v136, 0x44800000, v147
	v_fma_f32 v137, v113, s36, v142 clamp
	v_fmamk_f32 v147, v137, 0x45000000, v147
	s_cmp_eq_u32 s46, 3
	s_cbranch_scc1 .Lsel_mask_fin
	v_fma_f32 v134, v114, s36, v142 clamp
	v_fmamk_f32 v147, v134, 0x45800000, v147
	v_fma_f32 v135, v115, s36, v142 clamp
	v_fmamk_f32 v147, v135, 0x46000000, v147
	v_fma_f32 v136, v116, s36, v142 clamp
	v_fmamk_f32 v147, v136, 0x46800000, v147
	v_fma_f32 v137, v117, s36, v142 clamp
	v_fmamk_f32 v147, v137, 0x47000000, v147
	s_cmp_eq_u32 s46, 4
	s_cbranch_scc1 .Lsel_mask_fin
	v_fma_f32 v134, v118, s36, v142 clamp
	v_fmamk_f32 v148, v134, 0x3f800000, v148
	v_fma_f32 v135, v119, s36, v142 clamp
	v_fmamk_f32 v148, v135, 0x40000000, v148
	v_fma_f32 v136, v120, s36, v142 clamp
	v_fmamk_f32 v148, v136, 0x40800000, v148
	v_fma_f32 v137, v121, s36, v142 clamp
	v_fmamk_f32 v148, v137, 0x41000000, v148
	s_cmp_eq_u32 s46, 5
	s_cbranch_scc1 .Lsel_mask_fin
	v_fma_f32 v134, v122, s36, v142 clamp
	v_fmamk_f32 v148, v134, 0x41800000, v148
	v_fma_f32 v135, v123, s36, v142 clamp
	v_fmamk_f32 v148, v135, 0x42000000, v148
	v_fma_f32 v136, v124, s36, v142 clamp
	v_fmamk_f32 v148, v136, 0x42800000, v148
	v_fma_f32 v137, v125, s36, v142 clamp
	v_fmamk_f32 v148, v137, 0x43000000, v148
	s_cmp_eq_u32 s46, 6
	s_cbranch_scc1 .Lsel_mask_fin
	v_fma_f32 v134, v126, s36, v142 clamp
	v_fmamk_f32 v148, v134, 0x43800000, v148
	v_fma_f32 v135, v127, s36, v142 clamp
	v_fmamk_f32 v148, v135, 0x44000000, v148
	v_fma_f32 v136, v128, s36, v142 clamp
	v_fmamk_f32 v148, v136, 0x44800000, v148
	v_fma_f32 v137, v129, s36, v142 clamp
	v_fmamk_f32 v148, v137, 0x45000000, v148
	s_cmp_eq_u32 s46, 7
	s_cbranch_scc1 .Lsel_mask_fin
	v_fma_f32 v134, v130, s36, v142 clamp
	v_fmamk_f32 v148, v134, 0x45800000, v148
	v_fma_f32 v135, v131, s36, v142 clamp
	v_fmamk_f32 v148, v135, 0x46000000, v148
	v_fma_f32 v136, v132, s36, v142 clamp
	v_fmamk_f32 v148, v136, 0x46800000, v148
	v_fma_f32 v137, v133, s36, v142 clamp
	v_fmamk_f32 v148, v137, 0x47000000, v148
.Lsel_mask_fin:
	v_cvt_u32_f32_e32 v147, v147
	v_cvt_u32_f32_e32 v148, v148
	v_lshl_or_b32 v146, v148, 16, v147
	v_not_b32_e32 v146, v146
.Lsel_store:
	s_lshl_b32 s0, s46, 2
	s_sub_i32 s0, 32, s0
	s_lshr_b32 s1, -1, s0
	v_and_b32_e32 v146, s1, v146
	s_add_i32 s0, s27, s28
	s_lshl_b32 s0, s0, 8
	s_add_u32 s0, s0, 0x13000000
	s_add_u32 s42, s40, s0
	s_addc_u32 s43, s41, 0
	global_store_dword v152, v146, s[42:43]
	s_add_i32 s4, s4, 1
	s_cmp_lt_u32 s4, 2
	s_cbranch_scc1 .Lsel_row
	s_branch .LBB0_808

.Lcnt_red2:
	s_nop 7
	v_add_f32_dpp v138, v138, v138 quad_perm:[1,0,3,2] row_mask:0xf bank_mask:0xf bound_ctrl:1
	s_nop 1
	v_add_f32_dpp v138, v138, v138 quad_perm:[2,3,0,1] row_mask:0xf bank_mask:0xf bound_ctrl:1
	s_nop 1
	v_add_f32_dpp v138, v138, v138 row_half_mirror row_mask:0xf bank_mask:0xf bound_ctrl:1
	s_nop 1
	v_add_f32_dpp v138, v138, v138 row_mirror row_mask:0xf bank_mask:0xf bound_ctrl:1
	v_cvt_u32_f32_e32 v138, v138
	s_nop 0
	v_readfirstlane_b32 s0, v138
	s_sub_i32 s38, 0x100, s0
	s_mov_b32 s39, 0
	v_mov_b32_e32 v146, 0
	v_cmp_eq_f32_e64 s[42:43], v102, v150
	v_fma_f32 v134, v102, s37, -v142 clamp
	v_cvt_u32_f32_e32 v134, v134
	v_mbcnt_lo_u32_b32 v135, s42, 0
	v_mbcnt_hi_u32_b32 v135, s43, v135
	v_add_u32_e32 v135, s39, v135
	v_cmp_gt_u32_e32 vcc, s38, v135
	s_nop 1
	s_and_b64 vcc, vcc, s[42:43]
	s_nop 1
	v_cndmask_b32_e64 v136, 0, 1, vcc
	v_or_b32_e32 v136, v136, v134
	v_lshl_or_b32 v146, v136, 0, v146
	s_bcnt1_i32_b64 s0, s[42:43]
	s_add_i32 s39, s39, s0
	v_cmp_eq_f32_e64 s[42:43], v103, v150
	v_fma_f32 v134, v103, s37, -v142 clamp
	v_cvt_u32_f32_e32 v134, v134
	v_mbcnt_lo_u32_b32 v135, s42, 0
	v_mbcnt_hi_u32_b32 v135, s43, v135
	v_add_u32_e32 v135, s39, v135
	v_cmp_gt_u32_e32 vcc, s38, v135
	s_nop 1
	s_and_b64 vcc, vcc, s[42:43]
	s_nop 1
	v_cndmask_b32_e64 v136, 0, 1, vcc
	v_or_b32_e32 v136, v136, v134
	v_lshl_or_b32 v146, v136, 1, v146
	s_bcnt1_i32_b64 s0, s[42:43]
	s_add_i32 s39, s39, s0
	v_cmp_eq_f32_e64 s[42:43], v104, v150
	v_fma_f32 v134, v104, s37, -v142 clamp
	v_cvt_u32_f32_e32 v134, v134
	v_mbcnt_lo_u32_b32 v135, s42, 0
	v_mbcnt_hi_u32_b32 v135, s43, v135
	v_add_u32_e32 v135, s39, v135
	v_cmp_gt_u32_e32 vcc, s38, v135
	s_nop 1
	s_and_b64 vcc, vcc, s[42:43]
	s_nop 1
	v_cndmask_b32_e64 v136, 0, 1, vcc
	v_or_b32_e32 v136, v136, v134
	v_lshl_or_b32 v146, v136, 2, v146
	s_bcnt1_i32_b64 s0, s[42:43]
	s_add_i32 s39, s39, s0
	v_cmp_eq_f32_e64 s[42:43], v105, v150
	v_fma_f32 v134, v105, s37, -v142 clamp
	v_cvt_u32_f32_e32 v134, v134
	v_mbcnt_lo_u32_b32 v135, s42, 0
	v_mbcnt_hi_u32_b32 v135, s43, v135
	v_add_u32_e32 v135, s39, v135
	v_cmp_gt_u32_e32 vcc, s38, v135
	s_nop 1
	s_and_b64 vcc, vcc, s[42:43]
	s_nop 1
	v_cndmask_b32_e64 v136, 0, 1, vcc
	v_or_b32_e32 v136, v136, v134
	v_lshl_or_b32 v146, v136, 3, v146
	s_bcnt1_i32_b64 s0, s[42:43]
	s_add_i32 s39, s39, s0
	s_cmp_eq_u32 s46, 1
	s_cbranch_scc1 .Lsel_store
	v_cmp_eq_f32_e64 s[42:43], v106, v150
	v_fma_f32 v134, v106, s37, -v142 clamp
	v_cvt_u32_f32_e32 v134, v134
	v_mbcnt_lo_u32_b32 v135, s42, 0
	v_mbcnt_hi_u32_b32 v135, s43, v135
	v_add_u32_e32 v135, s39, v135
	v_cmp_gt_u32_e32 vcc, s38, v135
	s_nop 1
	s_and_b64 vcc, vcc, s[42:43]
	s_nop 1
	v_cndmask_b32_e64 v136, 0, 1, vcc
	v_or_b32_e32 v136, v136, v134
	v_lshl_or_b32 v146, v136, 4, v146
	s_bcnt1_i32_b64 s0, s[42:43]
	s_add_i32 s39, s39, s0
	v_cmp_eq_f32_e64 s[42:43], v107, v150
	v_fma_f32 v134, v107, s37, -v142 clamp
	v_cvt_u32_f32_e32 v134, v134
	v_mbcnt_lo_u32_b32 v135, s42, 0
	v_mbcnt_hi_u32_b32 v135, s43, v135
	v_add_u32_e32 v135, s39, v135
	v_cmp_gt_u32_e32 vcc, s38, v135
	s_nop 1
	s_and_b64 vcc, vcc, s[42:43]
	s_nop 1
	v_cndmask_b32_e64 v136, 0, 1, vcc
	v_or_b32_e32 v136, v136, v134
	v_lshl_or_b32 v146, v136, 5, v146
	s_bcnt1_i32_b64 s0, s[42:43]
	s_add_i32 s39, s39, s0
	v_cmp_eq_f32_e64 s[42:43], v108, v150
	v_fma_f32 v134, v108, s37, -v142 clamp
	v_cvt_u32_f32_e32 v134, v134
	v_mbcnt_lo_u32_b32 v135, s42, 0
	v_mbcnt_hi_u32_b32 v135, s43, v135
	v_add_u32_e32 v135, s39, v135
	v_cmp_gt_u32_e32 vcc, s38, v135
	s_nop 1
	s_and_b64 vcc, vcc, s[42:43]
	s_nop 1
	v_cndmask_b32_e64 v136, 0, 1, vcc
	v_or_b32_e32 v136, v136, v134
	v_lshl_or_b32 v146, v136, 6, v146
	s_bcnt1_i32_b64 s0, s[42:43]
	s_add_i32 s39, s39, s0
	v_cmp_eq_f32_e64 s[42:43], v109, v150
	v_fma_f32 v134, v109, s37, -v142 clamp
	v_cvt_u32_f32_e32 v134, v134
	v_mbcnt_lo_u32_b32 v135, s42, 0
	v_mbcnt_hi_u32_b32 v135, s43, v135
	v_add_u32_e32 v135, s39, v135
	v_cmp_gt_u32_e32 vcc, s38, v135
	s_nop 1
	s_and_b64 vcc, vcc, s[42:43]
	s_nop 1
	v_cndmask_b32_e64 v136, 0, 1, vcc
	v_or_b32_e32 v136, v136, v134
	v_lshl_or_b32 v146, v136, 7, v146
	s_bcnt1_i32_b64 s0, s[42:43]
	s_add_i32 s39, s39, s0
	s_cmp_eq_u32 s46, 2
	s_cbranch_scc1 .Lsel_store
	v_cmp_eq_f32_e64 s[42:43], v110, v150
	v_fma_f32 v134, v110, s37, -v142 clamp
	v_cvt_u32_f32_e32 v134, v134
	v_mbcnt_lo_u32_b32 v135, s42, 0
	v_mbcnt_hi_u32_b32 v135, s43, v135
	v_add_u32_e32 v135, s39, v135
	v_cmp_gt_u32_e32 vcc, s38, v135
	s_nop 1
	s_and_b64 vcc, vcc, s[42:43]
	s_nop 1
	v_cndmask_b32_e64 v136, 0, 1, vcc
	v_or_b32_e32 v136, v136, v134
	v_lshl_or_b32 v146, v136, 8, v146
	s_bcnt1_i32_b64 s0, s[42:43]
	s_add_i32 s39, s39, s0
	v_cmp_eq_f32_e64 s[42:43], v111, v150
	v_fma_f32 v134, v111, s37, -v142 clamp
	v_cvt_u32_f32_e32 v134, v134
	v_mbcnt_lo_u32_b32 v135, s42, 0
	v_mbcnt_hi_u32_b32 v135, s43, v135
	v_add_u32_e32 v135, s39, v135
	v_cmp_gt_u32_e32 vcc, s38, v135
	s_nop 1
	s_and_b64 vcc, vcc, s[42:43]
	s_nop 1
	v_cndmask_b32_e64 v136, 0, 1, vcc
	v_or_b32_e32 v136, v136, v134
	v_lshl_or_b32 v146, v136, 9, v146
	s_bcnt1_i32_b64 s0, s[42:43]
	s_add_i32 s39, s39, s0
	v_cmp_eq_f32_e64 s[42:43], v112, v150
	v_fma_f32 v134, v112, s37, -v142 clamp
	v_cvt_u32_f32_e32 v134, v134
	v_mbcnt_lo_u32_b32 v135, s42, 0
	v_mbcnt_hi_u32_b32 v135, s43, v135
	v_add_u32_e32 v135, s39, v135
	v_cmp_gt_u32_e32 vcc, s38, v135
	s_nop 1
	s_and_b64 vcc, vcc, s[42:43]
	s_nop 1
	v_cndmask_b32_e64 v136, 0, 1, vcc
	v_or_b32_e32 v136, v136, v134
	v_lshl_or_b32 v146, v136, 10, v146
	s_bcnt1_i32_b64 s0, s[42:43]
	s_add_i32 s39, s39, s0
	v_cmp_eq_f32_e64 s[42:43], v113, v150
	v_fma_f32 v134, v113, s37, -v142 clamp
	v_cvt_u32_f32_e32 v134, v134
	v_mbcnt_lo_u32_b32 v135, s42, 0
	v_mbcnt_hi_u32_b32 v135, s43, v135
	v_add_u32_e32 v135, s39, v135
	v_cmp_gt_u32_e32 vcc, s38, v135
	s_nop 1
	s_and_b64 vcc, vcc, s[42:43]
	s_nop 1
	v_cndmask_b32_e64 v136, 0, 1, vcc
	v_or_b32_e32 v136, v136, v134
	v_lshl_or_b32 v146, v136, 11, v146
	s_bcnt1_i32_b64 s0, s[42:43]
	s_add_i32 s39, s39, s0
	s_cmp_eq_u32 s46, 3
	s_cbranch_scc1 .Lsel_store
	v_cmp_eq_f32_e64 s[42:43], v114, v150
	v_fma_f32 v134, v114, s37, -v142 clamp
	v_cvt_u32_f32_e32 v134, v134
	v_mbcnt_lo_u32_b32 v135, s42, 0
	v_mbcnt_hi_u32_b32 v135, s43, v135
	v_add_u32_e32 v135, s39, v135
	v_cmp_gt_u32_e32 vcc, s38, v135
	s_nop 1
	s_and_b64 vcc, vcc, s[42:43]
	s_nop 1
	v_cndmask_b32_e64 v136, 0, 1, vcc
	v_or_b32_e32 v136, v136, v134
	v_lshl_or_b32 v146, v136, 12, v146
	s_bcnt1_i32_b64 s0, s[42:43]
	s_add_i32 s39, s39, s0
	v_cmp_eq_f32_e64 s[42:43], v115, v150
	v_fma_f32 v134, v115, s37, -v142 clamp
	v_cvt_u32_f32_e32 v134, v134
	v_mbcnt_lo_u32_b32 v135, s42, 0
	v_mbcnt_hi_u32_b32 v135, s43, v135
	v_add_u32_e32 v135, s39, v135
	v_cmp_gt_u32_e32 vcc, s38, v135
	s_nop 1
	s_and_b64 vcc, vcc, s[42:43]
	s_nop 1
	v_cndmask_b32_e64 v136, 0, 1, vcc
	v_or_b32_e32 v136, v136, v134
	v_lshl_or_b32 v146, v136, 13, v146
	s_bcnt1_i32_b64 s0, s[42:43]
	s_add_i32 s39, s39, s0
	v_cmp_eq_f32_e64 s[42:43], v116, v150
	v_fma_f32 v134, v116, s37, -v142 clamp
	v_cvt_u32_f32_e32 v134, v134
	v_mbcnt_lo_u32_b32 v135, s42, 0
	v_mbcnt_hi_u32_b32 v135, s43, v135
	v_add_u32_e32 v135, s39, v135
	v_cmp_gt_u32_e32 vcc, s38, v135
	s_nop 1
	s_and_b64 vcc, vcc, s[42:43]
	s_nop 1
	v_cndmask_b32_e64 v136, 0, 1, vcc
	v_or_b32_e32 v136, v136, v134
	v_lshl_or_b32 v146, v136, 14, v146
	s_bcnt1_i32_b64 s0, s[42:43]
	s_add_i32 s39, s39, s0
	v_cmp_eq_f32_e64 s[42:43], v117, v150
	v_fma_f32 v134, v117, s37, -v142 clamp
	v_cvt_u32_f32_e32 v134, v134
	v_mbcnt_lo_u32_b32 v135, s42, 0
	v_mbcnt_hi_u32_b32 v135, s43, v135
	v_add_u32_e32 v135, s39, v135
	v_cmp_gt_u32_e32 vcc, s38, v135
	s_nop 1
	s_and_b64 vcc, vcc, s[42:43]
	s_nop 1
	v_cndmask_b32_e64 v136, 0, 1, vcc
	v_or_b32_e32 v136, v136, v134
	v_lshl_or_b32 v146, v136, 15, v146
	s_bcnt1_i32_b64 s0, s[42:43]
	s_add_i32 s39, s39, s0
	s_cmp_eq_u32 s46, 4
	s_cbranch_scc1 .Lsel_store
	v_cmp_eq_f32_e64 s[42:43], v118, v150
	v_fma_f32 v134, v118, s37, -v142 clamp
	v_cvt_u32_f32_e32 v134, v134
	v_mbcnt_lo_u32_b32 v135, s42, 0
	v_mbcnt_hi_u32_b32 v135, s43, v135
	v_add_u32_e32 v135, s39, v135
	v_cmp_gt_u32_e32 vcc, s38, v135
	s_nop 1
	s_and_b64 vcc, vcc, s[42:43]
	s_nop 1
	v_cndmask_b32_e64 v136, 0, 1, vcc
	v_or_b32_e32 v136, v136, v134
	v_lshl_or_b32 v146, v136, 16, v146
	s_bcnt1_i32_b64 s0, s[42:43]
	s_add_i32 s39, s39, s0
	v_cmp_eq_f32_e64 s[42:43], v119, v150
	v_fma_f32 v134, v119, s37, -v142 clamp
	v_cvt_u32_f32_e32 v134, v134
	v_mbcnt_lo_u32_b32 v135, s42, 0
	v_mbcnt_hi_u32_b32 v135, s43, v135
	v_add_u32_e32 v135, s39, v135
	v_cmp_gt_u32_e32 vcc, s38, v135
	s_nop 1
	s_and_b64 vcc, vcc, s[42:43]
	s_nop 1
	v_cndmask_b32_e64 v136, 0, 1, vcc
	v_or_b32_e32 v136, v136, v134
	v_lshl_or_b32 v146, v136, 17, v146
	s_bcnt1_i32_b64 s0, s[42:43]
	s_add_i32 s39, s39, s0
	v_cmp_eq_f32_e64 s[42:43], v120, v150
	v_fma_f32 v134, v120, s37, -v142 clamp
	v_cvt_u32_f32_e32 v134, v134
	v_mbcnt_lo_u32_b32 v135, s42, 0
	v_mbcnt_hi_u32_b32 v135, s43, v135
	v_add_u32_e32 v135, s39, v135
	v_cmp_gt_u32_e32 vcc, s38, v135
	s_nop 1
	s_and_b64 vcc, vcc, s[42:43]
	s_nop 1
	v_cndmask_b32_e64 v136, 0, 1, vcc
	v_or_b32_e32 v136, v136, v134
	v_lshl_or_b32 v146, v136, 18, v146
	s_bcnt1_i32_b64 s0, s[42:43]
	s_add_i32 s39, s39, s0
	v_cmp_eq_f32_e64 s[42:43], v121, v150
	v_fma_f32 v134, v121, s37, -v142 clamp
	v_cvt_u32_f32_e32 v134, v134
	v_mbcnt_lo_u32_b32 v135, s42, 0
	v_mbcnt_hi_u32_b32 v135, s43, v135
	v_add_u32_e32 v135, s39, v135
	v_cmp_gt_u32_e32 vcc, s38, v135
	s_nop 1
	s_and_b64 vcc, vcc, s[42:43]
	s_nop 1
	v_cndmask_b32_e64 v136, 0, 1, vcc
	v_or_b32_e32 v136, v136, v134
	v_lshl_or_b32 v146, v136, 19, v146
	s_bcnt1_i32_b64 s0, s[42:43]
	s_add_i32 s39, s39, s0
	s_cmp_eq_u32 s46, 5
	s_cbranch_scc1 .Lsel_store
	v_cmp_eq_f32_e64 s[42:43], v122, v150
	v_fma_f32 v134, v122, s37, -v142 clamp
	v_cvt_u32_f32_e32 v134, v134
	v_mbcnt_lo_u32_b32 v135, s42, 0
	v_mbcnt_hi_u32_b32 v135, s43, v135
	v_add_u32_e32 v135, s39, v135
	v_cmp_gt_u32_e32 vcc, s38, v135
	s_nop 1
	s_and_b64 vcc, vcc, s[42:43]
	s_nop 1
	v_cndmask_b32_e64 v136, 0, 1, vcc
	v_or_b32_e32 v136, v136, v134
	v_lshl_or_b32 v146, v136, 20, v146
	s_bcnt1_i32_b64 s0, s[42:43]
	s_add_i32 s39, s39, s0
	v_cmp_eq_f32_e64 s[42:43], v123, v150
	v_fma_f32 v134, v123, s37, -v142 clamp
	v_cvt_u32_f32_e32 v134, v134
	v_mbcnt_lo_u32_b32 v135, s42, 0
	v_mbcnt_hi_u32_b32 v135, s43, v135
	v_add_u32_e32 v135, s39, v135
	v_cmp_gt_u32_e32 vcc, s38, v135
	s_nop 1
	s_and_b64 vcc, vcc, s[42:43]
	s_nop 1
	v_cndmask_b32_e64 v136, 0, 1, vcc
	v_or_b32_e32 v136, v136, v134
	v_lshl_or_b32 v146, v136, 21, v146
	s_bcnt1_i32_b64 s0, s[42:43]
	s_add_i32 s39, s39, s0
	v_cmp_eq_f32_e64 s[42:43], v124, v150
	v_fma_f32 v134, v124, s37, -v142 clamp
	v_cvt_u32_f32_e32 v134, v134
	v_mbcnt_lo_u32_b32 v135, s42, 0
	v_mbcnt_hi_u32_b32 v135, s43, v135
	v_add_u32_e32 v135, s39, v135
	v_cmp_gt_u32_e32 vcc, s38, v135
	s_nop 1
	s_and_b64 vcc, vcc, s[42:43]
	s_nop 1
	v_cndmask_b32_e64 v136, 0, 1, vcc
	v_or_b32_e32 v136, v136, v134
	v_lshl_or_b32 v146, v136, 22, v146
	s_bcnt1_i32_b64 s0, s[42:43]
	s_add_i32 s39, s39, s0
	v_cmp_eq_f32_e64 s[42:43], v125, v150
	v_fma_f32 v134, v125, s37, -v142 clamp
	v_cvt_u32_f32_e32 v134, v134
	v_mbcnt_lo_u32_b32 v135, s42, 0
	v_mbcnt_hi_u32_b32 v135, s43, v135
	v_add_u32_e32 v135, s39, v135
	v_cmp_gt_u32_e32 vcc, s38, v135
	s_nop 1
	s_and_b64 vcc, vcc, s[42:43]
	s_nop 1
	v_cndmask_b32_e64 v136, 0, 1, vcc
	v_or_b32_e32 v136, v136, v134
	v_lshl_or_b32 v146, v136, 23, v146
	s_bcnt1_i32_b64 s0, s[42:43]
	s_add_i32 s39, s39, s0
	s_cmp_eq_u32 s46, 6
	s_cbranch_scc1 .Lsel_store
	v_cmp_eq_f32_e64 s[42:43], v126, v150
	v_fma_f32 v134, v126, s37, -v142 clamp
	v_cvt_u32_f32_e32 v134, v134
	v_mbcnt_lo_u32_b32 v135, s42, 0
	v_mbcnt_hi_u32_b32 v135, s43, v135
	v_add_u32_e32 v135, s39, v135
	v_cmp_gt_u32_e32 vcc, s38, v135
	s_nop 1
	s_and_b64 vcc, vcc, s[42:43]
	s_nop 1
	v_cndmask_b32_e64 v136, 0, 1, vcc
	v_or_b32_e32 v136, v136, v134
	v_lshl_or_b32 v146, v136, 24, v146
	s_bcnt1_i32_b64 s0, s[42:43]
	s_add_i32 s39, s39, s0
	v_cmp_eq_f32_e64 s[42:43], v127, v150
	v_fma_f32 v134, v127, s37, -v142 clamp
	v_cvt_u32_f32_e32 v134, v134
	v_mbcnt_lo_u32_b32 v135, s42, 0
	v_mbcnt_hi_u32_b32 v135, s43, v135
	v_add_u32_e32 v135, s39, v135
	v_cmp_gt_u32_e32 vcc, s38, v135
	s_nop 1
	s_and_b64 vcc, vcc, s[42:43]
	s_nop 1
	v_cndmask_b32_e64 v136, 0, 1, vcc
	v_or_b32_e32 v136, v136, v134
	v_lshl_or_b32 v146, v136, 25, v146
	s_bcnt1_i32_b64 s0, s[42:43]
	s_add_i32 s39, s39, s0
	v_cmp_eq_f32_e64 s[42:43], v128, v150
	v_fma_f32 v134, v128, s37, -v142 clamp
	v_cvt_u32_f32_e32 v134, v134
	v_mbcnt_lo_u32_b32 v135, s42, 0
	v_mbcnt_hi_u32_b32 v135, s43, v135
	v_add_u32_e32 v135, s39, v135
	v_cmp_gt_u32_e32 vcc, s38, v135
	s_nop 1
	s_and_b64 vcc, vcc, s[42:43]
	s_nop 1
	v_cndmask_b32_e64 v136, 0, 1, vcc
	v_or_b32_e32 v136, v136, v134
	v_lshl_or_b32 v146, v136, 26, v146
	s_bcnt1_i32_b64 s0, s[42:43]
	s_add_i32 s39, s39, s0
	v_cmp_eq_f32_e64 s[42:43], v129, v150
	v_fma_f32 v134, v129, s37, -v142 clamp
	v_cvt_u32_f32_e32 v134, v134
	v_mbcnt_lo_u32_b32 v135, s42, 0
	v_mbcnt_hi_u32_b32 v135, s43, v135
	v_add_u32_e32 v135, s39, v135
	v_cmp_gt_u32_e32 vcc, s38, v135
	s_nop 1
	s_and_b64 vcc, vcc, s[42:43]
	s_nop 1
	v_cndmask_b32_e64 v136, 0, 1, vcc
	v_or_b32_e32 v136, v136, v134
	v_lshl_or_b32 v146, v136, 27, v146
	s_bcnt1_i32_b64 s0, s[42:43]
	s_add_i32 s39, s39, s0
	s_cmp_eq_u32 s46, 7
	s_cbranch_scc1 .Lsel_store
	v_cmp_eq_f32_e64 s[42:43], v130, v150
	v_fma_f32 v134, v130, s37, -v142 clamp
	v_cvt_u32_f32_e32 v134, v134
	v_mbcnt_lo_u32_b32 v135, s42, 0
	v_mbcnt_hi_u32_b32 v135, s43, v135
	v_add_u32_e32 v135, s39, v135
	v_cmp_gt_u32_e32 vcc, s38, v135
	s_nop 1
	s_and_b64 vcc, vcc, s[42:43]
	s_nop 1
	v_cndmask_b32_e64 v136, 0, 1, vcc
	v_or_b32_e32 v136, v136, v134
	v_lshl_or_b32 v146, v136, 28, v146
	s_bcnt1_i32_b64 s0, s[42:43]
	s_add_i32 s39, s39, s0
	v_cmp_eq_f32_e64 s[42:43], v131, v150
	v_fma_f32 v134, v131, s37, -v142 clamp
	v_cvt_u32_f32_e32 v134, v134
	v_mbcnt_lo_u32_b32 v135, s42, 0
	v_mbcnt_hi_u32_b32 v135, s43, v135
	v_add_u32_e32 v135, s39, v135
	v_cmp_gt_u32_e32 vcc, s38, v135
	s_nop 1
	s_and_b64 vcc, vcc, s[42:43]
	s_nop 1
	v_cndmask_b32_e64 v136, 0, 1, vcc
	v_or_b32_e32 v136, v136, v134
	v_lshl_or_b32 v146, v136, 29, v146
	s_bcnt1_i32_b64 s0, s[42:43]
	s_add_i32 s39, s39, s0
	v_cmp_eq_f32_e64 s[42:43], v132, v150
	v_fma_f32 v134, v132, s37, -v142 clamp
	v_cvt_u32_f32_e32 v134, v134
	v_mbcnt_lo_u32_b32 v135, s42, 0
	v_mbcnt_hi_u32_b32 v135, s43, v135
	v_add_u32_e32 v135, s39, v135
	v_cmp_gt_u32_e32 vcc, s38, v135
	s_nop 1
	s_and_b64 vcc, vcc, s[42:43]
	s_nop 1
	v_cndmask_b32_e64 v136, 0, 1, vcc
	v_or_b32_e32 v136, v136, v134
	v_lshl_or_b32 v146, v136, 30, v146
	s_bcnt1_i32_b64 s0, s[42:43]
	s_add_i32 s39, s39, s0
	v_cmp_eq_f32_e64 s[42:43], v133, v150
	v_fma_f32 v134, v133, s37, -v142 clamp
	v_cvt_u32_f32_e32 v134, v134
	v_mbcnt_lo_u32_b32 v135, s42, 0
	v_mbcnt_hi_u32_b32 v135, s43, v135
	v_add_u32_e32 v135, s39, v135
	v_cmp_gt_u32_e32 vcc, s38, v135
	s_nop 1
	s_and_b64 vcc, vcc, s[42:43]
	s_nop 1
	v_cndmask_b32_e64 v136, 0, 1, vcc
	v_or_b32_e32 v136, v136, v134
	v_lshl_or_b32 v146, v136, 31, v146
	s_bcnt1_i32_b64 s0, s[42:43]
	s_add_i32 s39, s39, s0
	s_branch .Lsel_store
